# in-proj and MLP-in GEMMs: next row tile's row-statistics prep moved out of the main loop into the epilogue start (two lanes per row, DPP combine; no mid-loop vmcnt(0) drain)
# speedup vs baseline: 1.0009x; 1.0009x over previous
; #define LAS __attribute__((address_space(3)))
; __device__ __forceinline__ int tidx() { int t = threadIdx.x; asm volatile("" : "+v"(t)); return t; }
; __device__ __forceinline__ int prow0(int pm) { return (pm >> 4) * LP + PADR + (pm & 15) * 256; }
; __device__ __forceinline__ int trow(int i) { return (i >> 4) * LP + 4144 + (i & 15); }
;     __device__ __forceinline__ ColInfo colinfo(int col) const { ColInfo c; c.a = (f32x4){0.f, 0.f, 0.f, 0.f}; c.b = c.a; if (fold) { c.a = *(const f32x4*)(c1 + col); c.b = *(const f32x4*)(c2 + col); } return c; }
; __device__ __forceinline__ void prep_rowstats(const float* stat, int pm, int par, LAS unsigned char* lds) {
;     const int t = tidx();
;     if (t < (pm < 64 ? 256 : 64)) {
;         const int row = pm < 64 ? prow0(pm) + t : trow(t); const f32x4* sp = (const f32x4*)(stat + (size_t)row * 32);
;         float s1 = 0.f, s2 = 0.f;
; #pragma unroll
;         for (int q = 0; q < 8; ++q) { const f32x4 v = sp[q]; s1 += v[0] + v[2]; s2 += v[1] + v[3]; }
;         const float mu = s1 * (1.0f / 1024.0f); const float var = fmaxf(s2 * (1.0f / 1024.0f) - mu * mu, 0.f);
;         ((LAS f32x2*)(lds + RS_OFF + par * 2048))[t] = (f32x2){mu, __builtin_amdgcn_rsqf(var + LN_EPS)};
;     }
; }
; template <class Epi>
; __device__ __forceinline__ void gemm_phase(LAS unsigned char* lds, const bf16_t* Ag, const bf16_t* Btg, const int K, const int nM, const int nN, const Epi& E) {
;     ...
;         {
;             ColInfo ci[2][2];
; #pragma unroll
;             for (int bj = 0; bj < 2; ++bj)
; #pragma unroll
;                 for (int n = 0; n < 2; ++n) ci[bj][n] = E.colinfo(pn * 256 + bj * 128 + wc * 32 + n * 16 + fq * 4);
;             u32x2 pk[4][2][2];
; #pragma unroll
;             for (int gi = 0; gi < 8; ++gi) {
;                 const int ai = gi >> 2, m = gi & 3;
;                 const int lrow = ai * 128 + wr * 64 + m * 16 + fr, row = prow0(pm) + lrow;
.LBB0_82:
	s_and_b64 vcc, exec, s[48:49]
	s_cbranch_vccnz .Lprep5_a
	v_lshrrev_b32_e32 v226, 1, v198
	v_and_b32_e32 v227, 1, v198
	v_add_u32_e32 v228, s46, v226
	v_lshlrev_b32_e32 v228, 7, v228
	v_lshl_add_u32 v228, v227, 6, v228
	v_mov_b32_e32 v229, 0
	v_lshl_add_u64 v[228:229], s[18:19], 0, v[228:229]
	global_load_dwordx4 v[232:235], v[228:229], off
	global_load_dwordx4 v[236:239], v[228:229], off offset:16
	global_load_dwordx4 v[240:243], v[228:229], off offset:32
	global_load_dwordx4 v[244:247], v[228:229], off offset:48
	v_lshl_add_u32 v226, v226, 3, s70
.Lprep5_a:
	v_lshl_or_b32 v188, s68, 8, v185
	v_ashrrev_i32_e32 v189, 31, v188
	v_lshlrev_b64 v[124:125], 2, v[188:189]
	v_lshl_add_u64 v[126:127], s[6:7], 0, v[124:125]
	v_lshl_add_u64 v[124:125], s[22:23], 0, v[124:125]
	global_load_dwordx4 v[148:151], v[126:127], off
	global_load_dwordx4 v[156:159], v[124:125], off
	v_or_b32_e32 v124, 16, v188
	v_ashrrev_i32_e32 v125, 31, v124
	v_lshlrev_b64 v[124:125], 2, v[124:125]
	v_lshl_add_u64 v[126:127], s[6:7], 0, v[124:125]
	v_lshl_add_u64 v[124:125], s[22:23], 0, v[124:125]
	global_load_dwordx4 v[136:139], v[126:127], off
	global_load_dwordx4 v[140:143], v[124:125], off
	v_or_b32_e32 v124, 0x80, v188
	v_ashrrev_i32_e32 v125, 31, v124
	v_lshlrev_b64 v[124:125], 2, v[124:125]
	v_lshl_add_u64 v[126:127], s[6:7], 0, v[124:125]
	v_lshl_add_u64 v[124:125], s[22:23], 0, v[124:125]
	global_load_dwordx4 v[128:131], v[126:127], off
	global_load_dwordx4 v[132:135], v[124:125], off
	v_or_b32_e32 v124, 0x90, v188
	v_ashrrev_i32_e32 v125, 31, v124
	v_lshlrev_b64 v[152:153], 2, v[124:125]
	v_lshl_add_u64 v[124:125], s[6:7], 0, v[152:153]
	global_load_dwordx4 v[124:127], v[124:125], off
	v_lshl_add_u64 v[152:153], s[22:23], 0, v[152:153]
	global_load_dwordx4 v[152:155], v[152:153], off
	s_lshr_b32 s12, s66, 4
	s_lshl_b32 s15, s66, 8
	s_mulk_i32 s12, 0x1040
	s_and_b32 s15, s15, 0xf00
	s_add_i32 s15, s15, s12
	s_add_i32 s12, s14, 0
	s_add_i32 s12, s12, 0x20000
	v_lshl_add_u32 v187, v174, 3, s12
	ds_read_b64 v[172:173], v187
	s_or_b32 s15, s15, 48
	v_add_u32_e32 v190, s15, v174
	v_ashrrev_i32_e32 v191, 31, v190
	v_lshlrev_b64 v[190:191], 13, v[190:191]
	s_waitcnt vmcnt(0)
	s_cmp_lg_u32 s48, 0
	s_cbranch_scc1 .Lprep5_b
	v_pk_add_f32 v[248:249], v[232:233], v[234:235]
	v_pk_add_f32 v[250:251], v[236:237], v[238:239]
	v_pk_add_f32 v[248:249], v[248:249], v[250:251]
	v_pk_add_f32 v[250:251], v[240:241], v[242:243]
	v_pk_add_f32 v[248:249], v[248:249], v[250:251]
	v_pk_add_f32 v[250:251], v[244:245], v[246:247]
	v_pk_add_f32 v[248:249], v[248:249], v[250:251]
	s_nop 1
	v_mov_b32_dpp v250, v248 quad_perm:[1,0,3,2] row_mask:0xf bank_mask:0xf
	v_mov_b32_dpp v251, v249 quad_perm:[1,0,3,2] row_mask:0xf bank_mask:0xf
	s_nop 0
	v_pk_add_f32 v[248:249], v[248:249], v[250:251]
	v_pk_mul_f32 v[248:249], v[248:249], s[0:1] op_sel_hi:[1,0]
	s_nop 0
	v_fma_f32 v249, -v248, v248, v249
	v_max_f32_e32 v249, 0, v249
	v_add_f32_e32 v249, 0x3727c5ac, v249
	v_rsq_f32_e32 v249, v249
	s_nop 0
	ds_write_b64 v226, v[248:249]

; __device__ __forceinline__ int prow0(int pm) { return (pm >> 4) * LP + PADR + (pm & 15) * 256; }
;     __device__ __forceinline__ void prep(int pm, int par, LAS unsigned char* lds) const { if (fold) prep_rowstats(stat, pm, par, lds); }
;     __device__ __forceinline__ void prep(int pm, int par, LAS unsigned char* lds) const { if (!ident) prep_rowstats(stat, pm, par, lds); }
;     __device__ __forceinline__ void prep(int pm, int par, LAS unsigned char* lds) const { prep_rowstats(stat, pm, par, lds); }
; #define G_STAGE(bufoff, gbase) do { _Pragma("unroll") for (int _i = 0; _i < 2; ++_i) \
;         __builtin_amdgcn_global_load_lds((const unsigned*)((const char*)(gbase) + voff[_i]), (LAS unsigned*)(lds + (bufoff) + ldsw + _i * 8192), 16, 0, 0); } while (0)
; #define G_WAIT_L(n) asm volatile("s_waitcnt lgkmcnt(" #n ")" ::: "memory")
; #define G_BAR __builtin_amdgcn_s_barrier()
; template <class Epi>
; __device__ __forceinline__ void gemm_phase(LAS unsigned char* lds, const bf16_t* Ag, const bf16_t* Btg, const int K, const int nM, const int nN, const Epi& E) {
;     ...
;         const int un = u + G; const bool has_next = un < nunits; const int pmn = has_next ? un % nM : pm, pnn = has_next ? un / nM : pn;
;         const char* nA = has_next ? (const char*)Ag + (size_t)prow0(pmn) * rstep : cA; const char* nB = has_next ? (const char*)Btg + (size_t)pnn * tstep : cB;
;         for (int t = 0; t < nt; t += 2) {
;             const bool last = (t == nt - 2);
;             const char* a1 = cA + (size_t)(t + 1) * kstep;
;             const char* a2 = last ? nA : cA + (size_t)(t + 2) * kstep; const char* b2 = last ? nB : cB + (size_t)(t + 2) * kstep;
;             const char* a3 = a2 + kstep; const char* b3 = b2 + kstep;
;             if (last && has_next && pmn != pm) E.prep(pmn, par ^ 1, lds);
;             G_LDB(B0, 0, 0); G_SCHED; G_LDA(At, 0, 0); G_STAGE(G_SA(1, 1), a1 + hstep);
;             G_WAIT_L(8); G_BAR; G_WAIT_L(0); G_MMA(0, 0, At, B0); G_BAR; G_SCHED;
;     ...
; #pragma unroll
;         for (int a = 0; a < 2; ++a)
; #pragma unroll
;             for (int b = 0; b < 2; ++b)
; #pragma unroll
;                 for (int m = 0; m < 4; ++m)
; #pragma unroll
;                     for (int n = 0; n < 2; ++n) acc[a][b][m][n] = (f32x4){0.f, 0.f, 0.f, 0.f};
;         if (pmn != pm) par ^= 1;
;         u = un; pm = pmn; pn = pnn; cA = nA; cB = nB;
.LBB0_846:
	s_ashr_i32 s47, s26, 6
	s_and_b64 s[14:15], s[48:49], exec
	s_cselect_b32 s14, s69, s47
	s_ashr_i32 s15, s14, 31
	s_lshl_b64 s[14:15], s[14:15], 19
	s_add_u32 s44, s6, s14
	s_addc_u32 s45, s7, s15
	s_and_b64 s[14:15], s[48:49], exec
	s_cselect_b32 s14, s53, s45
	s_cselect_b32 s15, s52, s44
	s_cmp_eq_u32 s67, s68
	s_cselect_b64 s[54:55], -1, 0
	s_or_b64 s[54:55], s[42:43], s[54:55]
	v_lshlrev_b32_e32 v174, 11, v223
	s_or_b64 s[48:49], s[48:49], s[54:55]
	v_xor_b32_e32 v8, 0x800, v174
	s_add_u32 s70, s52, 0x100
	v_add_u32_e32 v8, 0, v8
	s_addc_u32 s71, s53, 0
	v_add_u32_e32 v128, 0x20000, v8
	s_add_u32 s50, s50, 0x40080
	v_mov_b32_e32 v8, 0
	s_addc_u32 s51, s51, 0
	s_mov_b32 s72, -2
	v_mov_b32_e32 v9, v8
	v_mov_b32_e32 v10, v8
	v_mov_b32_e32 v11, v8
	v_mov_b32_e32 v12, v8
	v_mov_b32_e32 v13, v8
	v_mov_b32_e32 v14, v8
	v_mov_b32_e32 v15, v8
	v_mov_b32_e32 v24, v8
	v_mov_b32_e32 v25, v8
	v_mov_b32_e32 v26, v8
	v_mov_b32_e32 v27, v8
	v_mov_b32_e32 v28, v8
	v_mov_b32_e32 v29, v8
	v_mov_b32_e32 v30, v8
	v_mov_b32_e32 v31, v8
	v_mov_b32_e32 v40, v8
	v_mov_b32_e32 v41, v8
	v_mov_b32_e32 v42, v8
	v_mov_b32_e32 v43, v8
	v_mov_b32_e32 v44, v8
	v_mov_b32_e32 v45, v8
	v_mov_b32_e32 v46, v8
	v_mov_b32_e32 v47, v8
	v_mov_b32_e32 v56, v8
	v_mov_b32_e32 v57, v8
	v_mov_b32_e32 v58, v8
	v_mov_b32_e32 v59, v8
	v_mov_b32_e32 v60, v8
	v_mov_b32_e32 v61, v8
	v_mov_b32_e32 v62, v8
	v_mov_b32_e32 v63, v8
	v_mov_b32_e32 v72, v8
	v_mov_b32_e32 v73, v8
	v_mov_b32_e32 v74, v8
	v_mov_b32_e32 v75, v8
	v_mov_b32_e32 v76, v8
	v_mov_b32_e32 v77, v8
	v_mov_b32_e32 v78, v8
	v_mov_b32_e32 v79, v8
	v_mov_b32_e32 v88, v8
	v_mov_b32_e32 v89, v8
	v_mov_b32_e32 v90, v8
	v_mov_b32_e32 v91, v8
	v_mov_b32_e32 v92, v8
	v_mov_b32_e32 v93, v8
	v_mov_b32_e32 v94, v8
	v_mov_b32_e32 v95, v8
	v_mov_b32_e32 v104, v8
	v_mov_b32_e32 v105, v8
	v_mov_b32_e32 v106, v8
	v_mov_b32_e32 v107, v8
	v_mov_b32_e32 v108, v8
	v_mov_b32_e32 v109, v8
	v_mov_b32_e32 v110, v8
	v_mov_b32_e32 v111, v8
	v_mov_b32_e32 v120, v8
	v_mov_b32_e32 v121, v8
	v_mov_b32_e32 v122, v8
	v_mov_b32_e32 v123, v8
	v_mov_b32_e32 v124, v8
	v_mov_b32_e32 v125, v8
	v_mov_b32_e32 v126, v8
	v_mov_b32_e32 v127, v8
	v_mov_b32_e32 v80, v8
	v_mov_b32_e32 v81, v8
	v_mov_b32_e32 v82, v8
	v_mov_b32_e32 v83, v8
	v_mov_b32_e32 v84, v8
	v_mov_b32_e32 v85, v8
	v_mov_b32_e32 v86, v8
	v_mov_b32_e32 v87, v8
	v_mov_b32_e32 v96, v8
	v_mov_b32_e32 v97, v8
	v_mov_b32_e32 v98, v8
	v_mov_b32_e32 v99, v8
	v_mov_b32_e32 v100, v8
	v_mov_b32_e32 v101, v8
	v_mov_b32_e32 v102, v8
	v_mov_b32_e32 v103, v8
	v_mov_b32_e32 v112, v8
	v_mov_b32_e32 v113, v8
	v_mov_b32_e32 v114, v8
	v_mov_b32_e32 v115, v8
	v_mov_b32_e32 v116, v8
	v_mov_b32_e32 v117, v8
	v_mov_b32_e32 v118, v8
	v_mov_b32_e32 v119, v8
	v_mov_b32_e32 v140, v8
	v_mov_b32_e32 v141, v8
	v_mov_b32_e32 v142, v8
	v_mov_b32_e32 v143, v8
	v_mov_b32_e32 v152, v8
	v_mov_b32_e32 v153, v8
	v_mov_b32_e32 v154, v8
	v_mov_b32_e32 v155, v8
	v_mov_b32_e32 v68, v8
	v_mov_b32_e32 v69, v8
	v_mov_b32_e32 v70, v8
	v_mov_b32_e32 v71, v8
	v_mov_b32_e32 v64, v8
	v_mov_b32_e32 v65, v8
	v_mov_b32_e32 v66, v8
	v_mov_b32_e32 v67, v8
	v_mov_b32_e32 v52, v8
	v_mov_b32_e32 v53, v8
	v_mov_b32_e32 v54, v8
	v_mov_b32_e32 v55, v8
	v_mov_b32_e32 v48, v8
	v_mov_b32_e32 v49, v8
	v_mov_b32_e32 v50, v8
	v_mov_b32_e32 v51, v8
	v_mov_b32_e32 v36, v8
	v_mov_b32_e32 v37, v8
	v_mov_b32_e32 v38, v8
	v_mov_b32_e32 v39, v8
	v_mov_b32_e32 v32, v8
	v_mov_b32_e32 v33, v8
	v_mov_b32_e32 v34, v8
	v_mov_b32_e32 v35, v8
	v_mov_b32_e32 v20, v8
	v_mov_b32_e32 v21, v8
	v_mov_b32_e32 v22, v8
	v_mov_b32_e32 v23, v8
	v_mov_b32_e32 v16, v8
	v_mov_b32_e32 v17, v8
	v_mov_b32_e32 v18, v8
	v_mov_b32_e32 v19, v8
	s_branch .LBB0_849
.LBB0_848:
	s_add_u32 s26, s50, 0xfffc0080
	s_addc_u32 s54, s51, -1
	s_and_b64 s[52:53], s[52:53], exec
	s_cselect_b32 s55, s54, s25
	s_cselect_b32 s54, s26, s24
	s_cselect_b32 s53, s71, s14
	s_cselect_b32 s52, s70, s15
	s_add_i32 s26, 0, 0x10000
	v_add_u32_e32 v129, s26, v179
	ds_read_b128 v[130:133], v129
	ds_read_b128 v[134:137], v129 offset:1024
	ds_read_b128 v[144:147], v129 offset:2048
	ds_read_b128 v[148:151], v129 offset:3072
	v_lshl_add_u64 v[138:139], s[50:51], 0, v[170:171]
	s_add_i32 m0, s60, 0xc000
	ds_read_b128 v[156:159], v222
	ds_read_b128 v[160:163], v222 offset:1024
	ds_read_b128 v[164:167], v222 offset:2048
	ds_read_b128 v[180:183], v222 offset:3072
	ds_read_b128 v[184:187], v222 offset:4096
	ds_read_b128 v[224:227], v222 offset:5120
	ds_read_b128 v[228:231], v222 offset:6144
	ds_read_b128 v[232:235], v222 offset:7168
	global_load_lds_dwordx4 v[138:139], off
	v_lshl_add_u64 v[138:139], s[50:51], 0, v[168:169]
	s_add_i32 m0, s60, 0xe000
	s_nop 0
	global_load_lds_dwordx4 v[138:139], off
	s_waitcnt lgkmcnt(8)
	s_barrier
	s_waitcnt lgkmcnt(0)
	s_setprio 1
	s_waitcnt lgkmcnt(0)
	v_mfma_f32_16x16x32_bf16 v[152:155], v[130:133], v[156:159], v[152:155]
	v_mfma_f32_16x16x32_bf16 v[138:141], v[144:147], v[156:159], v[140:143]
	v_mfma_f32_16x16x32_bf16 v[116:119], v[130:133], v[164:167], v[116:119]
	v_mfma_f32_16x16x32_bf16 v[112:115], v[144:147], v[164:167], v[112:115]
	v_mfma_f32_16x16x32_bf16 v[100:103], v[130:133], v[184:187], v[100:103]
	v_mfma_f32_16x16x32_bf16 v[96:99], v[144:147], v[184:187], v[96:99]
	v_mfma_f32_16x16x32_bf16 v[84:87], v[130:133], v[228:231], v[84:87]
	v_mfma_f32_16x16x32_bf16 v[80:83], v[144:147], v[228:231], v[80:83]
	v_mfma_f32_16x16x32_bf16 v[152:155], v[134:137], v[160:163], v[152:155]
	v_mfma_f32_16x16x32_bf16 v[138:141], v[148:151], v[160:163], v[138:141]
	v_mfma_f32_16x16x32_bf16 v[116:119], v[134:137], v[180:183], v[116:119]
	v_mfma_f32_16x16x32_bf16 v[112:115], v[148:151], v[180:183], v[112:115]
	v_mfma_f32_16x16x32_bf16 v[100:103], v[134:137], v[224:227], v[100:103]
	v_mfma_f32_16x16x32_bf16 v[96:99], v[148:151], v[224:227], v[96:99]
	v_mfma_f32_16x16x32_bf16 v[84:87], v[134:137], v[232:235], v[84:87]
	v_mfma_f32_16x16x32_bf16 v[80:83], v[148:151], v[232:235], v[80:83]
	s_setprio 0
	s_barrier
; #define G_STAGE(bufoff, gbase) do { _Pragma("unroll") for (int _i = 0; _i < 2; ++_i) \
;         __builtin_amdgcn_global_load_lds((const unsigned*)((const char*)(gbase) + voff[_i]), (LAS unsigned*)(lds + (bufoff) + ldsw + _i * 8192), 16, 0, 0); } while (0)
; #define G_LDA(dst, b, h) do { _Pragma("unroll") for (int m = 0; m < 4; ++m) _Pragma("unroll") for (int k = 0; k < 2; ++k) dst[m][k] = *(const LAS bf16x8*)(lds + G_SA(b, h) + aoff + m * 2048 + k * 1024); } while (0)
; #define G_LDB(dst, b, h) do { _Pragma("unroll") for (int n = 0; n < 2; ++n) _Pragma("unroll") for (int k = 0; k < 2; ++k) dst[n][k] = *(const LAS bf16x8*)(lds + G_SB(b, h) + boff + n * 2048 + k * 1024); } while (0)
; #define G_MMA(ai, bj, At, Bt) do { __builtin_amdgcn_s_setprio(1); _Pragma("unroll") for (int m = 0; m < 4; ++m) _Pragma("unroll") for (int n = 0; n < 2; ++n) _Pragma("unroll") for (int k = 0; k < 2; ++k) \
;         acc[ai][bj][m][n] = MFMA16(Bt[n][k], At[m][k], acc[ai][bj][m][n]); __builtin_amdgcn_s_setprio(0); } while (0)
; #define G_WAIT_V(n) asm volatile("s_waitcnt vmcnt(" #n ")" ::: "memory")
; #define G_WAIT_L(n) asm volatile("s_waitcnt lgkmcnt(" #n ")" ::: "memory")
; #define G_BAR __builtin_amdgcn_s_barrier()
; #define G_SCHED __builtin_amdgcn_sched_barrier(0)
; template <class Epi>
; __device__ __forceinline__ void gemm_phase(LAS unsigned char* lds, const bf16_t* Ag, const bf16_t* Btg, const int K, const int nM, const int nN, const Epi& E) {
;     ...
;             G_LDB(B1, 0, 1); G_STAGE(G_SB(0, 0), b2);
;             G_BAR; G_WAIT_L(0); G_MMA(0, 1, At, B1); G_BAR;
;             G_LDA(At, 0, 1); G_STAGE(G_SA(0, 0), a2);
;             G_BAR; G_WAIT_L(0); G_MMA(1, 0, At, B0); G_BAR; G_SCHED;
;             G_STAGE(G_SB(0, 1), b2 + hstep);
;             G_WAIT_V(6); G_BAR; G_MMA(1, 1, At, B1); G_BAR;
;             G_LDB(B0, 1, 0); G_SCHED; G_LDA(At, 1, 0); G_STAGE(G_SA(0, 1), a2 + hstep);
;             G_WAIT_L(8); G_BAR; G_WAIT_L(0); G_MMA(0, 0, At, B0); G_BAR; G_SCHED;
	s_add_i32 s73, 0, 0x14000
	s_add_i32 s26, s26, s59
	v_add_u32_e32 v129, s73, v179
	v_lshl_add_u64 v[172:173], s[52:53], 0, v[0:1]
	s_mov_b32 m0, s26
	ds_read_b128 v[236:239], v129
	ds_read_b128 v[240:243], v129 offset:1024
	ds_read_b128 v[244:247], v129 offset:2048
	ds_read_b128 v[248:251], v129 offset:3072
	global_load_lds_dwordx4 v[172:173], off
	v_lshl_add_u64 v[188:189], s[52:53], 0, v[2:3]
	s_add_i32 m0, s26, 0x2000
	s_nop 0
	global_load_lds_dwordx4 v[188:189], off
	s_barrier
	s_waitcnt lgkmcnt(0)
	s_setprio 1
	s_waitcnt lgkmcnt(0)
	v_mfma_f32_16x16x32_bf16 v[124:127], v[236:239], v[156:159], v[124:127]
	v_mfma_f32_16x16x32_bf16 v[120:123], v[244:247], v[156:159], v[120:123]
	v_mfma_f32_16x16x32_bf16 v[108:111], v[236:239], v[164:167], v[108:111]
	v_mfma_f32_16x16x32_bf16 v[104:107], v[244:247], v[164:167], v[104:107]
	v_mfma_f32_16x16x32_bf16 v[92:95], v[236:239], v[184:187], v[92:95]
	v_mfma_f32_16x16x32_bf16 v[88:91], v[244:247], v[184:187], v[88:91]
	v_mfma_f32_16x16x32_bf16 v[76:79], v[236:239], v[228:231], v[76:79]
	v_mfma_f32_16x16x32_bf16 v[72:75], v[244:247], v[228:231], v[72:75]
	v_mfma_f32_16x16x32_bf16 v[124:127], v[240:243], v[160:163], v[124:127]
	v_mfma_f32_16x16x32_bf16 v[120:123], v[248:251], v[160:163], v[120:123]
	v_mfma_f32_16x16x32_bf16 v[108:111], v[240:243], v[180:183], v[108:111]
	v_mfma_f32_16x16x32_bf16 v[104:107], v[248:251], v[180:183], v[104:107]
	v_mfma_f32_16x16x32_bf16 v[92:95], v[240:243], v[224:227], v[92:95]
	v_mfma_f32_16x16x32_bf16 v[88:91], v[248:251], v[224:227], v[88:91]
	v_mfma_f32_16x16x32_bf16 v[76:79], v[240:243], v[232:235], v[76:79]
	v_mfma_f32_16x16x32_bf16 v[72:75], v[248:251], v[232:235], v[72:75]
	s_setprio 0
	s_mov_b32 m0, s60
	v_lshl_add_u64 v[210:211], s[54:55], 0, v[0:1]
	s_barrier
	ds_read_b128 v[156:159], v222 offset:16384
	ds_read_b128 v[160:163], v222 offset:17408
	ds_read_b128 v[164:167], v222 offset:18432
	ds_read_b128 v[180:183], v222 offset:19456
	ds_read_b128 v[184:187], v222 offset:20480
	ds_read_b128 v[224:227], v222 offset:21504
	ds_read_b128 v[228:231], v222 offset:22528
	ds_read_b128 v[232:235], v222 offset:23552
	global_load_lds_dwordx4 v[210:211], off
	v_lshl_add_u64 v[216:217], s[54:55], 0, v[2:3]
	s_mov_b32 m0, s61
	s_nop 0
	global_load_lds_dwordx4 v[216:217], off
	s_barrier
	s_waitcnt lgkmcnt(0)
	s_setprio 1
	s_waitcnt lgkmcnt(0)
	v_mfma_f32_16x16x32_bf16 v[60:63], v[130:133], v[156:159], v[60:63]
	v_mfma_f32_16x16x32_bf16 v[56:59], v[144:147], v[156:159], v[56:59]
	v_mfma_f32_16x16x32_bf16 v[44:47], v[130:133], v[164:167], v[44:47]
	v_mfma_f32_16x16x32_bf16 v[40:43], v[144:147], v[164:167], v[40:43]
	v_mfma_f32_16x16x32_bf16 v[28:31], v[130:133], v[184:187], v[28:31]
	v_mfma_f32_16x16x32_bf16 v[24:27], v[144:147], v[184:187], v[24:27]
	v_mfma_f32_16x16x32_bf16 v[12:15], v[130:133], v[228:231], v[12:15]
	v_mfma_f32_16x16x32_bf16 v[8:11], v[144:147], v[228:231], v[8:11]
	v_mfma_f32_16x16x32_bf16 v[60:63], v[134:137], v[160:163], v[60:63]
	v_mfma_f32_16x16x32_bf16 v[56:59], v[148:151], v[160:163], v[56:59]
	v_mfma_f32_16x16x32_bf16 v[44:47], v[134:137], v[180:183], v[44:47]
	v_mfma_f32_16x16x32_bf16 v[40:43], v[148:151], v[180:183], v[40:43]
	v_mfma_f32_16x16x32_bf16 v[28:31], v[134:137], v[224:227], v[28:31]
	v_mfma_f32_16x16x32_bf16 v[24:27], v[148:151], v[224:227], v[24:27]
	v_mfma_f32_16x16x32_bf16 v[12:15], v[134:137], v[232:235], v[12:15]
	v_mfma_f32_16x16x32_bf16 v[8:11], v[148:151], v[232:235], v[8:11]
	s_setprio 0
	s_barrier
	s_add_u32 s74, s52, 0x40000
	s_addc_u32 s75, s53, 0
	s_add_i32 s26, s73, s59
	v_lshl_add_u64 v[130:131], s[74:75], 0, v[0:1]
	s_mov_b32 m0, s26
	s_nop 0
	global_load_lds_dwordx4 v[130:131], off
	v_lshl_add_u64 v[130:131], s[74:75], 0, v[2:3]
	s_add_i32 m0, s26, 0x2000
	s_nop 0
	global_load_lds_dwordx4 v[130:131], off
	s_waitcnt vmcnt(6)
	s_barrier
	s_setprio 1
	v_mfma_f32_16x16x32_bf16 v[68:71], v[236:239], v[156:159], v[68:71]
	v_mfma_f32_16x16x32_bf16 v[64:67], v[244:247], v[156:159], v[64:67]
	v_mfma_f32_16x16x32_bf16 v[52:55], v[236:239], v[164:167], v[52:55]
	v_mfma_f32_16x16x32_bf16 v[48:51], v[244:247], v[164:167], v[48:51]
	v_mfma_f32_16x16x32_bf16 v[36:39], v[236:239], v[184:187], v[36:39]
	v_mfma_f32_16x16x32_bf16 v[32:35], v[244:247], v[184:187], v[32:35]
	v_mfma_f32_16x16x32_bf16 v[20:23], v[236:239], v[228:231], v[20:23]
	v_mfma_f32_16x16x32_bf16 v[16:19], v[244:247], v[228:231], v[16:19]
	v_mfma_f32_16x16x32_bf16 v[68:71], v[240:243], v[160:163], v[68:71]
	v_mfma_f32_16x16x32_bf16 v[64:67], v[248:251], v[160:163], v[64:67]
	v_mfma_f32_16x16x32_bf16 v[52:55], v[240:243], v[180:183], v[52:55]
	v_mfma_f32_16x16x32_bf16 v[48:51], v[248:251], v[180:183], v[48:51]
	v_mfma_f32_16x16x32_bf16 v[36:39], v[240:243], v[224:227], v[36:39]
	v_mfma_f32_16x16x32_bf16 v[32:35], v[248:251], v[224:227], v[32:35]
	v_mfma_f32_16x16x32_bf16 v[20:23], v[240:243], v[232:235], v[20:23]
	v_mfma_f32_16x16x32_bf16 v[16:19], v[248:251], v[232:235], v[16:19]
	s_setprio 0
	s_add_i32 s26, 0, 0x18000
	v_add_u32_e32 v129, s26, v179
	s_barrier
	ds_read_b128 v[130:133], v129
	ds_read_b128 v[134:137], v129 offset:1024
	ds_read_b128 v[144:147], v129 offset:2048
	ds_read_b128 v[148:151], v129 offset:3072
	s_add_u32 s54, s54, 0x40000
	s_addc_u32 s55, s55, 0
	s_mov_b32 m0, s62
	v_lshl_add_u64 v[142:143], s[54:55], 0, v[0:1]
	ds_read_b128 v[156:159], v222 offset:32768
	ds_read_b128 v[160:163], v222 offset:33792
	ds_read_b128 v[164:167], v222 offset:34816
	ds_read_b128 v[180:183], v222 offset:35840
	ds_read_b128 v[184:187], v222 offset:36864
	ds_read_b128 v[224:227], v222 offset:37888
	ds_read_b128 v[228:231], v222 offset:38912
	ds_read_b128 v[232:235], v222 offset:39936
	global_load_lds_dwordx4 v[142:143], off
	v_lshl_add_u64 v[142:143], s[54:55], 0, v[2:3]
	s_mov_b32 m0, s63
	s_nop 0
	global_load_lds_dwordx4 v[142:143], off
	s_waitcnt lgkmcnt(8)
	s_barrier
; #define G_STAGE(bufoff, gbase) do { _Pragma("unroll") for (int _i = 0; _i < 2; ++_i) \
;         __builtin_amdgcn_global_load_lds((const unsigned*)((const char*)(gbase) + voff[_i]), (LAS unsigned*)(lds + (bufoff) + ldsw + _i * 8192), 16, 0, 0); } while (0)
; #define G_LDA(dst, b, h) do { _Pragma("unroll") for (int m = 0; m < 4; ++m) _Pragma("unroll") for (int k = 0; k < 2; ++k) dst[m][k] = *(const LAS bf16x8*)(lds + G_SA(b, h) + aoff + m * 2048 + k * 1024); } while (0)
; #define G_LDB(dst, b, h) do { _Pragma("unroll") for (int n = 0; n < 2; ++n) _Pragma("unroll") for (int k = 0; k < 2; ++k) dst[n][k] = *(const LAS bf16x8*)(lds + G_SB(b, h) + boff + n * 2048 + k * 1024); } while (0)
; #define G_MMA(ai, bj, At, Bt) do { __builtin_amdgcn_s_setprio(1); _Pragma("unroll") for (int m = 0; m < 4; ++m) _Pragma("unroll") for (int n = 0; n < 2; ++n) _Pragma("unroll") for (int k = 0; k < 2; ++k) \
;         acc[ai][bj][m][n] = MFMA16(Bt[n][k], At[m][k], acc[ai][bj][m][n]); __builtin_amdgcn_s_setprio(0); } while (0)
; #define G_WAIT_V(n) asm volatile("s_waitcnt vmcnt(" #n ")" ::: "memory")
; #define G_WAIT_L(n) asm volatile("s_waitcnt lgkmcnt(" #n ")" ::: "memory")
; #define G_BAR __builtin_amdgcn_s_barrier()
; #define G_SCHED __builtin_amdgcn_sched_barrier(0)
; template <class Epi>
; __device__ __forceinline__ void gemm_phase(LAS unsigned char* lds, const bf16_t* Ag, const bf16_t* Btg, const int K, const int nM, const int nN, const Epi& E) {
;     ...
;             G_WAIT_L(8); G_BAR; G_WAIT_L(0); G_MMA(0, 0, At, B0); G_BAR; G_SCHED;
;             G_LDB(B1, 1, 1); G_STAGE(G_SB(1, 0), b3);
;             G_BAR; G_WAIT_L(0); G_MMA(0, 1, At, B1); G_BAR;
;             G_LDA(At, 1, 1); G_STAGE(G_SA(1, 0), a3);
;             G_BAR; G_WAIT_L(0); G_MMA(1, 0, At, B0); G_BAR; G_SCHED;
;             G_STAGE(G_SB(1, 1), b3 + hstep);
;             G_WAIT_V(6); G_BAR; G_MMA(1, 1, At, B1); G_BAR;
;         }
	s_waitcnt lgkmcnt(0)
	s_setprio 1
	s_waitcnt lgkmcnt(0)
	v_mfma_f32_16x16x32_bf16 v[152:155], v[130:133], v[156:159], v[152:155]
	v_mfma_f32_16x16x32_bf16 v[138:141], v[144:147], v[156:159], v[138:141]
	v_mfma_f32_16x16x32_bf16 v[116:119], v[130:133], v[164:167], v[116:119]
	v_mfma_f32_16x16x32_bf16 v[112:115], v[144:147], v[164:167], v[112:115]
	v_mfma_f32_16x16x32_bf16 v[100:103], v[130:133], v[184:187], v[100:103]
	v_mfma_f32_16x16x32_bf16 v[96:99], v[144:147], v[184:187], v[96:99]
	v_mfma_f32_16x16x32_bf16 v[84:87], v[130:133], v[228:231], v[84:87]
	v_mfma_f32_16x16x32_bf16 v[80:83], v[144:147], v[228:231], v[80:83]
	v_mfma_f32_16x16x32_bf16 v[152:155], v[134:137], v[160:163], v[152:155]
	v_mfma_f32_16x16x32_bf16 v[140:143], v[148:151], v[160:163], v[138:141]
	v_mfma_f32_16x16x32_bf16 v[116:119], v[134:137], v[180:183], v[116:119]
	v_mfma_f32_16x16x32_bf16 v[112:115], v[148:151], v[180:183], v[112:115]
	v_mfma_f32_16x16x32_bf16 v[100:103], v[134:137], v[224:227], v[100:103]
	v_mfma_f32_16x16x32_bf16 v[96:99], v[148:151], v[224:227], v[96:99]
	v_mfma_f32_16x16x32_bf16 v[84:87], v[134:137], v[232:235], v[84:87]
	v_mfma_f32_16x16x32_bf16 v[80:83], v[148:151], v[232:235], v[80:83]
	s_setprio 0
	s_barrier
	s_add_i32 s54, 0, 0x1c000
	s_add_i32 s26, s26, s59
	v_add_u32_e32 v129, s54, v179
	v_lshl_add_u64 v[138:139], v[172:173], 0, s[94:95]
	s_mov_b32 m0, s26
	ds_read_b128 v[236:239], v129
	ds_read_b128 v[240:243], v129 offset:1024
	ds_read_b128 v[244:247], v129 offset:2048
	ds_read_b128 v[248:251], v129 offset:3072
	global_load_lds_dwordx4 v[138:139], off
	v_lshl_add_u64 v[138:139], v[188:189], 0, s[94:95]
	s_add_i32 m0, s26, 0x2000
	s_nop 0
	global_load_lds_dwordx4 v[138:139], off
	s_barrier
	s_waitcnt lgkmcnt(0)
	s_setprio 1
	s_waitcnt lgkmcnt(0)
	v_mfma_f32_16x16x32_bf16 v[124:127], v[236:239], v[156:159], v[124:127]
	v_mfma_f32_16x16x32_bf16 v[120:123], v[244:247], v[156:159], v[120:123]
	v_mfma_f32_16x16x32_bf16 v[108:111], v[236:239], v[164:167], v[108:111]
	v_mfma_f32_16x16x32_bf16 v[104:107], v[244:247], v[164:167], v[104:107]
	v_mfma_f32_16x16x32_bf16 v[92:95], v[236:239], v[184:187], v[92:95]
	v_mfma_f32_16x16x32_bf16 v[88:91], v[244:247], v[184:187], v[88:91]
	v_mfma_f32_16x16x32_bf16 v[76:79], v[236:239], v[228:231], v[76:79]
	v_mfma_f32_16x16x32_bf16 v[72:75], v[244:247], v[228:231], v[72:75]
	v_mfma_f32_16x16x32_bf16 v[124:127], v[240:243], v[160:163], v[124:127]
	v_mfma_f32_16x16x32_bf16 v[120:123], v[248:251], v[160:163], v[120:123]
	v_mfma_f32_16x16x32_bf16 v[108:111], v[240:243], v[180:183], v[108:111]
	v_mfma_f32_16x16x32_bf16 v[104:107], v[248:251], v[180:183], v[104:107]
	v_mfma_f32_16x16x32_bf16 v[92:95], v[240:243], v[224:227], v[92:95]
	v_mfma_f32_16x16x32_bf16 v[88:91], v[248:251], v[224:227], v[88:91]
	v_mfma_f32_16x16x32_bf16 v[76:79], v[240:243], v[232:235], v[76:79]
	v_mfma_f32_16x16x32_bf16 v[72:75], v[248:251], v[232:235], v[72:75]
	s_setprio 0
	s_mov_b32 m0, s64
	v_lshl_add_u64 v[138:139], v[210:211], 0, s[94:95]
	s_barrier
	ds_read_b128 v[156:159], v222 offset:49152
	ds_read_b128 v[160:163], v222 offset:50176
	ds_read_b128 v[164:167], v222 offset:51200
	ds_read_b128 v[180:183], v222 offset:52224
	ds_read_b128 v[184:187], v222 offset:53248
	ds_read_b128 v[224:227], v222 offset:54272
	ds_read_b128 v[228:231], v222 offset:55296
	ds_read_b128 v[232:235], v222 offset:56320
	global_load_lds_dwordx4 v[138:139], off
	v_lshl_add_u64 v[138:139], v[216:217], 0, s[94:95]
	s_mov_b32 m0, s65
	s_nop 0
	global_load_lds_dwordx4 v[138:139], off
	s_barrier
	s_waitcnt lgkmcnt(0)
	s_setprio 1
	s_waitcnt lgkmcnt(0)
	v_mfma_f32_16x16x32_bf16 v[60:63], v[130:133], v[156:159], v[60:63]
	v_mfma_f32_16x16x32_bf16 v[56:59], v[144:147], v[156:159], v[56:59]
	v_mfma_f32_16x16x32_bf16 v[44:47], v[130:133], v[164:167], v[44:47]
	v_mfma_f32_16x16x32_bf16 v[40:43], v[144:147], v[164:167], v[40:43]
	v_mfma_f32_16x16x32_bf16 v[28:31], v[130:133], v[184:187], v[28:31]
	v_mfma_f32_16x16x32_bf16 v[24:27], v[144:147], v[184:187], v[24:27]
	v_mfma_f32_16x16x32_bf16 v[12:15], v[130:133], v[228:231], v[12:15]
	v_mfma_f32_16x16x32_bf16 v[8:11], v[144:147], v[228:231], v[8:11]
	v_mfma_f32_16x16x32_bf16 v[60:63], v[134:137], v[160:163], v[60:63]
	v_mfma_f32_16x16x32_bf16 v[56:59], v[148:151], v[160:163], v[56:59]
	v_mfma_f32_16x16x32_bf16 v[44:47], v[134:137], v[180:183], v[44:47]
	v_mfma_f32_16x16x32_bf16 v[40:43], v[148:151], v[180:183], v[40:43]
	v_mfma_f32_16x16x32_bf16 v[28:31], v[134:137], v[224:227], v[28:31]
	v_mfma_f32_16x16x32_bf16 v[24:27], v[148:151], v[224:227], v[24:27]
	v_mfma_f32_16x16x32_bf16 v[12:15], v[134:137], v[232:235], v[12:15]
	v_mfma_f32_16x16x32_bf16 v[8:11], v[148:151], v[232:235], v[8:11]
	s_setprio 0
	s_barrier
	s_add_u32 s52, s52, 0x40080
	s_addc_u32 s53, s53, 0
	s_add_i32 s26, s54, s59
	v_lshl_add_u64 v[130:131], s[52:53], 0, v[0:1]
	s_mov_b32 m0, s26
	s_nop 0
	global_load_lds_dwordx4 v[130:131], off
	v_lshl_add_u64 v[130:131], s[52:53], 0, v[2:3]
	s_add_i32 m0, s26, 0x2000
	s_nop 0
	global_load_lds_dwordx4 v[130:131], off
	s_waitcnt vmcnt(6)
	s_barrier
	s_setprio 1
	v_mfma_f32_16x16x32_bf16 v[68:71], v[236:239], v[156:159], v[68:71]
	v_mfma_f32_16x16x32_bf16 v[64:67], v[244:247], v[156:159], v[64:67]
	v_mfma_f32_16x16x32_bf16 v[52:55], v[236:239], v[164:167], v[52:55]
	v_mfma_f32_16x16x32_bf16 v[48:51], v[244:247], v[164:167], v[48:51]
	v_mfma_f32_16x16x32_bf16 v[36:39], v[236:239], v[184:187], v[36:39]
	v_mfma_f32_16x16x32_bf16 v[32:35], v[244:247], v[184:187], v[32:35]
	v_mfma_f32_16x16x32_bf16 v[20:23], v[236:239], v[228:231], v[20:23]
	v_mfma_f32_16x16x32_bf16 v[16:19], v[244:247], v[228:231], v[16:19]
	v_mfma_f32_16x16x32_bf16 v[68:71], v[240:243], v[160:163], v[68:71]
	v_mfma_f32_16x16x32_bf16 v[64:67], v[248:251], v[160:163], v[64:67]
	v_mfma_f32_16x16x32_bf16 v[52:55], v[240:243], v[180:183], v[52:55]
	v_mfma_f32_16x16x32_bf16 v[48:51], v[248:251], v[180:183], v[48:51]
	v_mfma_f32_16x16x32_bf16 v[36:39], v[240:243], v[224:227], v[36:39]
	v_mfma_f32_16x16x32_bf16 v[32:35], v[248:251], v[224:227], v[32:35]
	v_mfma_f32_16x16x32_bf16 v[20:23], v[240:243], v[232:235], v[20:23]
	v_mfma_f32_16x16x32_bf16 v[16:19], v[248:251], v[232:235], v[16:19]
	s_setprio 0
	s_add_i32 s72, s72, 2
	s_add_u32 s70, s70, 0x100
	s_addc_u32 s71, s71, 0
	s_add_u32 s50, s50, 0x100
	s_addc_u32 s51, s51, 0
	s_cmp_gt_u32 s72, 13
	s_barrier
	s_cbranch_scc1 .LBB0_852
; #define LAS __attribute__((address_space(3)))
; __device__ __forceinline__ int tidx() { int t = threadIdx.x; asm volatile("" : "+v"(t)); return t; }
; __device__ __forceinline__ int prow0(int pm) { return (pm >> 4) * LP + PADR + (pm & 15) * 256; }
; __device__ __forceinline__ int trow(int i) { return (i >> 4) * LP + 4144 + (i & 15); }
;     __device__ __forceinline__ void prep(int pm, int par, LAS unsigned char* lds) const { if (fold) prep_rowstats(stat, pm, par, lds); }
;     __device__ __forceinline__ void prep(int pm, int par, LAS unsigned char* lds) const { if (!ident) prep_rowstats(stat, pm, par, lds); }
;     __device__ __forceinline__ void prep(int pm, int par, LAS unsigned char* lds) const { prep_rowstats(stat, pm, par, lds); }
; __device__ __forceinline__ void prep_rowstats(const float* stat, int pm, int par, LAS unsigned char* lds) {
;     const int t = tidx();
;     if (t < (pm < 64 ? 256 : 64)) {
;         const int row = pm < 64 ? prow0(pm) + t : trow(t); const f32x4* sp = (const f32x4*)(stat + (size_t)row * 32);
;         float s1 = 0.f, s2 = 0.f;
; #pragma unroll
;         for (int q = 0; q < 8; ++q) { const f32x4 v = sp[q]; s1 += v[0] + v[2]; s2 += v[1] + v[3]; }
;         const float mu = s1 * (1.0f / 1024.0f); const float var = fmaxf(s2 * (1.0f / 1024.0f) - mu * mu, 0.f);
;         ((LAS f32x2*)(lds + RS_OFF + par * 2048))[t] = (f32x2){mu, __builtin_amdgcn_rsqf(var + LN_EPS)};
; template <class Epi>
; __device__ __forceinline__ void gemm_phase(LAS unsigned char* lds, const bf16_t* Ag, const bf16_t* Btg, const int K, const int nM, const int nN, const Epi& E) {
;     ...
;         for (int t = 0; t < nt; t += 2) {
;             const bool last = (t == nt - 2);
;             const char* a1 = cA + (size_t)(t + 1) * kstep;
;             const char* a2 = last ? nA : cA + (size_t)(t + 2) * kstep; const char* b2 = last ? nB : cB + (size_t)(t + 2) * kstep;
;             const char* a3 = a2 + kstep; const char* b3 = b2 + kstep;
;             if (last && has_next && pmn != pm) E.prep(pmn, par ^ 1, lds);
.LBB0_849:
	s_cmp_lg_u32 s72, 12
	s_cselect_b64 s[52:53], -1, 0
	s_or_b64 s[54:55], s[48:49], s[52:53]
	s_and_b64 vcc, exec, s[54:55]
	s_branch .LBB0_848
.LBB0_852:
	s_and_b64 vcc, exec, s[48:49]
	s_cbranch_vccnz .Lprep0_a
	v_lshrrev_b32_e32 v226, 1, v198
	v_and_b32_e32 v227, 1, v198
	v_add_u32_e32 v228, s46, v226
	v_lshlrev_b32_e32 v228, 7, v228
	v_lshl_add_u32 v228, v227, 6, v228
	v_mov_b32_e32 v229, 0
	v_lshl_add_u64 v[228:229], s[34:35], 0, v[228:229]
	global_load_dwordx4 v[232:235], v[228:229], off
	global_load_dwordx4 v[236:239], v[228:229], off offset:16
	global_load_dwordx4 v[240:243], v[228:229], off offset:32
	global_load_dwordx4 v[244:247], v[228:229], off offset:48
	v_lshl_add_u32 v226, v226, 3, v128

; #define LAS __attribute__((address_space(3)))
; __device__ __forceinline__ u32x2 pack4(const f32x4 a) { u32x2 v; v.x = cvt_pk_bf16(a[0], a[1]); v.y = cvt_pk_bf16(a[2], a[3]); return v; }
;     __device__ __forceinline__ f32x4 preload(int row, int col) const { const u32x2 w = *(const u32x2*)(xb + (size_t)row * DM + col); return (f32x4){bflo(w.x), bfhi(w.x), bflo(w.y), bfhi(w.y)}; }
;     __device__ __forceinline__ f32x4 preload(int row, int col) const { return (f32x4){0.f, 0.f, 0.f, 0.f}; }
;     __device__ __forceinline__ u32x2 preload_pk(int row, int col) const { return (u32x2){0u, 0u}; }
; __device__ __forceinline__ void prep_rowstats(const float* stat, int pm, int par, LAS unsigned char* lds) {
;     ...
;         for (int q = 0; q < 8; ++q) { const f32x4 v = sp[q]; s1 += v[0] + v[2]; s2 += v[1] + v[3]; }
;         const float mu = s1 * (1.0f / 1024.0f); const float var = fmaxf(s2 * (1.0f / 1024.0f) - mu * mu, 0.f);
;         ((LAS f32x2*)(lds + RS_OFF + par * 2048))[t] = (f32x2){mu, __builtin_amdgcn_rsqf(var + LN_EPS)};
;     __device__ __forceinline__ RowInfo rowinfo(int row, int lrow, int par, LAS unsigned char* lds) const {
;         RowInfo r; r.mu = 0.f; r.rstd = 1.f; if (fold) { const f32x2 sv = ((const LAS f32x2*)(lds + RS_OFF + par * 2048))[lrow]; r.mu = sv.x; r.rstd = sv.y; }
;         r.pad = 0; return r; }
;     __device__ __forceinline__ ColInfo colinfo(int col) const { ColInfo c; c.a = (f32x4){0.f, 0.f, 0.f, 0.f}; c.b = c.a; if (fold) { c.a = *(const f32x4*)(c1 + col); c.b = *(const f32x4*)(c2 + col); } return c; }
;     __device__ __forceinline__ f32x4 preload(int row, int col) const { return (f32x4){0.f, 0.f, 0.f, 0.f}; }
;     __device__ __forceinline__ u32x2 preload_pk(int row, int col) const { return (u32x2){0u, 0u}; }
;     __device__ __forceinline__ void apply(const RowInfo& ri, const ColInfo& ci, int row, int col, f32x4 a, f32x4 pv, float& s1, float& s2) const {
;         f32x4 v = a;
;         if (fold) v = (a - ci.a * ri.mu) * ri.rstd + ci.b;
;         if (ri.pad) v = (f32x4){0.f, 0.f, 0.f, 0.f};
;         *(u32x2*)(proj + (size_t)row * NPROJ + col) = pack4(v);
;     }
.LBB0_862:
	s_lshr_b32 s14, s68, 4
	s_lshl_b32 s15, s68, 8
	s_waitcnt vmcnt(0)
	s_cmp_lg_u32 s48, 0
	s_cbranch_scc1 .Lprep0_b
	v_pk_add_f32 v[248:249], v[232:233], v[234:235]
	v_pk_add_f32 v[250:251], v[236:237], v[238:239]
	v_pk_add_f32 v[248:249], v[248:249], v[250:251]
	v_pk_add_f32 v[250:251], v[240:241], v[242:243]
	v_pk_add_f32 v[248:249], v[248:249], v[250:251]
	v_pk_add_f32 v[250:251], v[244:245], v[246:247]
	v_pk_add_f32 v[248:249], v[248:249], v[250:251]
	s_nop 1
	v_mov_b32_dpp v250, v248 quad_perm:[1,0,3,2] row_mask:0xf bank_mask:0xf
	v_mov_b32_dpp v251, v249 quad_perm:[1,0,3,2] row_mask:0xf bank_mask:0xf
	s_nop 0
	v_pk_add_f32 v[248:249], v[248:249], v[250:251]
	v_pk_mul_f32 v[248:249], v[248:249], s[0:1] op_sel_hi:[1,0]
	s_nop 0
	v_fma_f32 v249, -v248, v248, v249
	v_max_f32_e32 v249, 0, v249
	v_add_f32_e32 v249, 0x3727c5ac, v249
	v_rsq_f32_e32 v249, v249
	s_nop 0
	ds_write_b64 v226, v[248:249]
.Lprep0_b:
	v_xor_b32_e32 v139, 0x80000000, v139
	v_xor_b32_e32 v138, 0x80000000, v138
	v_xor_b32_e32 v217, 0x80000000, v137
	v_xor_b32_e32 v216, 0x80000000, v136
	s_mulk_i32 s14, 0x1040
	s_and_b32 s15, s15, 0xf00
	v_pk_fma_f32 v[210:211], v[138:139], v[188:189], v[154:155]
	v_pk_fma_f32 v[216:217], v[216:217], v[184:185], v[152:153]
	s_add_i32 s15, s15, s14
	v_pk_fma_f32 v[216:217], v[182:183], v[216:217], v[132:133]
	v_pk_fma_f32 v[210:211], v[186:187], v[210:211], v[134:135]
	s_or_b32 s14, s15, 48
	v_cndmask_b32_e64 v155, v211, v155, s[42:43]
	v_cndmask_b32_e64 v154, v210, v154, s[42:43]
	v_cndmask_b32_e64 v153, v217, v153, s[42:43]
	v_cndmask_b32_e64 v152, v216, v152, s[42:43]
	v_add_u32_e32 v175, s14, v176
	v_cvt_pk_bf16_f32 v152, v152, v153
	v_cvt_pk_bf16_f32 v153, v154, v155
	v_mov_b64_e32 v[154:155], s[86:87]
	v_mad_i64_i32 v[154:155], s[48:49], v175, s9, v[154:155]
	v_lshl_add_u64 v[154:155], v[172:173], 1, v[154:155]
	v_xor_b32_e32 v131, 0x80000000, v131
	v_xor_b32_e32 v130, 0x80000000, v130
	v_xor_b32_e32 v211, 0x80000000, v129
	v_xor_b32_e32 v210, 0x80000000, v128
	global_store_dwordx2 v[154:155], v[152:153], off
	v_pk_fma_f32 v[152:153], v[130:131], v[188:189], v[142:143]
	v_pk_fma_f32 v[210:211], v[210:211], v[184:185], v[140:141]
	v_pk_fma_f32 v[152:153], v[186:187], v[152:153], v[146:147]
	v_pk_fma_f32 v[210:211], v[182:183], v[210:211], v[144:145]
	v_cndmask_b32_e64 v143, v153, v143, s[42:43]
	v_cndmask_b32_e64 v142, v152, v142, s[42:43]
	v_cndmask_b32_e64 v141, v211, v141, s[42:43]
	v_cndmask_b32_e64 v140, v210, v140, s[42:43]
	v_cvt_pk_bf16_f32 v140, v140, v141
	v_cvt_pk_bf16_f32 v141, v142, v143
	global_store_dwordx2 v[154:155], v[140:141], off offset:32
	v_xor_b32_e32 v141, 0x80000000, v159
	v_xor_b32_e32 v140, 0x80000000, v158
	v_xor_b32_e32 v153, 0x80000000, v157
	v_xor_b32_e32 v152, 0x80000000, v156
	v_pk_fma_f32 v[142:143], v[140:141], v[188:189], v[126:127]
	v_pk_fma_f32 v[152:153], v[152:153], v[184:185], v[124:125]
	v_pk_fma_f32 v[142:143], v[186:187], v[142:143], v[162:163]
	v_pk_fma_f32 v[152:153], v[182:183], v[152:153], v[160:161]
	v_cndmask_b32_e64 v127, v143, v127, s[42:43]
	v_cndmask_b32_e64 v126, v142, v126, s[42:43]
	v_cndmask_b32_e64 v125, v153, v125, s[42:43]
	v_cndmask_b32_e64 v124, v152, v124, s[42:43]
	v_cvt_pk_bf16_f32 v124, v124, v125
	v_cvt_pk_bf16_f32 v125, v126, v127
	global_store_dwordx2 v[154:155], v[124:125], off offset:256
	v_xor_b32_e32 v125, 0x80000000, v151
	v_xor_b32_e32 v124, 0x80000000, v150
	v_xor_b32_e32 v143, 0x80000000, v149
	v_xor_b32_e32 v142, 0x80000000, v148
	v_pk_fma_f32 v[126:127], v[124:125], v[188:189], v[122:123]
	v_pk_fma_f32 v[142:143], v[142:143], v[184:185], v[120:121]
	v_pk_fma_f32 v[126:127], v[186:187], v[126:127], v[166:167]
	v_pk_fma_f32 v[142:143], v[182:183], v[142:143], v[164:165]
	v_cndmask_b32_e64 v123, v127, v123, s[42:43]
	v_cndmask_b32_e64 v122, v126, v122, s[42:43]
	v_cndmask_b32_e64 v121, v143, v121, s[42:43]
	v_cndmask_b32_e64 v120, v142, v120, s[42:43]
	v_cvt_pk_bf16_f32 v120, v120, v121
	v_cvt_pk_bf16_f32 v121, v122, v123
	global_store_dwordx2 v[154:155], v[120:121], off offset:288
	s_and_b64 vcc, exec, s[40:41]
	v_mov_b32_e32 v181, 0
	v_mov_b32_e32 v120, 0
	v_mov_b32_e32 v121, 0
	v_mov_b32_e32 v175, 1.0
	v_mov_b32_e32 v122, 1.0
	v_mov_b32_e32 v123, 1.0
	s_cbranch_vccnz .LBB0_864
	ds_read_b64 v[174:175], v225 offset:128
	s_waitcnt lgkmcnt(0)
	v_mov_b32_e32 v180, v174
	v_mov_b32_e32 v181, v174
	v_mov_b32_e32 v120, v174
	v_mov_b32_e32 v121, v174
	v_mov_b32_e32 v174, v175
	v_mov_b32_e32 v122, v175
	v_mov_b32_e32 v123, v175
